# set0->set1 column tile move plus barrier after rwkv prep: GEMM blocks arrive without waiting
# baseline (speedup 1.0000x reference)
; __device__ __forceinline__ unsigned xb_ld(unsigned* p)              { return __hip_atomic_load(p, __ATOMIC_RELAXED, __HIP_MEMORY_SCOPE_AGENT); }
; __device__ __forceinline__ unsigned xb_add(unsigned* p, unsigned v) { return __hip_atomic_fetch_add(p, v, __ATOMIC_RELAXED, __HIP_MEMORY_SCOPE_AGENT); }
; #define XB_SPIN(cond, bar) do { unsigned _sp = 0; while (cond) { __builtin_amdgcn_s_sleep(1); \
;     if ((++_sp & 255u) == 0u) { if (xb_ld(&(bar)[XB_TMO])) break; if (_sp > XB_SPIN_CAP) { atomicAdd(&(bar)[XB_TMO], 1u); break; } } } } while (0)
; __device__ __forceinline__ void xcd_barrier(const XcdBarrier& b) {
;     ...
;         const unsigned old = xb_add(&bar[XB_XSUB(b.x)], 1u);
;         const unsigned gen = old / nloc;
;         if (old + 1u == (gen + 1u) * nloc) {
;             __builtin_amdgcn_fence(__ATOMIC_RELEASE, "agent");
;             asm volatile("s_waitcnt vmcnt(0)" ::: "memory");
;             const unsigned og = xb_add(&bar[XB_TOP], 1u);
;             const unsigned tg = og / nx;
;             if (og + 1u == (tg + 1u) * nx) xb_add(&bar[XB_TOPGEN], 1u);
;             else XB_SPIN(xb_ld(&bar[XB_TOPGEN]) == tg, bar);
;             __builtin_amdgcn_fence(__ATOMIC_ACQUIRE, "agent");
;             xb_add(&bar[XB_XGEN(b.x)], 1u);
;             asm volatile("s_waitcnt vmcnt(0)" ::: "memory");
;         } else {
;             XB_SPIN(xb_ld(&bar[XB_XGEN(b.x)]) == gen, bar);
.LBB0_525:
	s_or_b64 exec, exec, s[10:11]
	v_cvt_f32_u32_e32 v4, v2
	s_waitcnt vmcnt(0)
	v_readfirstlane_b32 s0, v3
	v_sub_u32_e32 v3, 0, v2
	v_rcp_iflag_f32_e32 v4, v4
	v_add_u32_e32 v5, s0, v1
	v_mul_f32_e32 v4, 0x4f7ffffe, v4
	v_cvt_u32_f32_e32 v4, v4
	v_mul_lo_u32 v1, v3, v4
	v_mul_hi_u32 v1, v4, v1
	v_add_u32_e32 v1, v4, v1
	v_mul_hi_u32 v1, v5, v1
	v_mul_lo_u32 v3, v1, v2
	v_sub_u32_e32 v3, v5, v3
	v_add_u32_e32 v4, 1, v1
	v_cmp_ge_u32_e32 vcc, v3, v2
	s_nop 1
	v_cndmask_b32_e32 v1, v1, v4, vcc
	v_sub_u32_e32 v4, v3, v2
	v_cndmask_b32_e32 v3, v3, v4, vcc
	v_add_u32_e32 v4, 1, v1
	v_cmp_ge_u32_e32 vcc, v3, v2
	v_add_u32_e32 v3, 1, v5
	s_nop 0
	v_cndmask_b32_e32 v1, v1, v4, vcc
	v_mul_lo_u32 v4, v2, v1
	v_add_u32_e32 v2, v4, v2
	v_cmp_ne_u32_e32 vcc, v3, v2
	s_and_saveexec_b64 s[0:1], vcc
	s_xor_b64 s[6:7], exec, s[0:1]
	s_cbranch_execz .LBB0_539
	s_waitcnt lgkmcnt(0)
	s_cmpk_gt_i32 s33, 0x80
	s_cbranch_scc0 .Lb2wait_l0
	s_cmp_gt_i32 s92, 63
	s_cbranch_scc1 .LBB0_539
.Lb2wait_l0:
	v_mov_b32_e32 v0, 0x2000
	global_load_dword v0, v0, s[4:5] offset:1024 sc1
	s_add_u32 s52, s4, 0x2400
	s_addc_u32 s53, s5, 0
	s_waitcnt vmcnt(0)
	v_cmp_eq_u32_e32 vcc, v0, v1
	s_and_saveexec_b64 s[10:11], vcc
	s_cbranch_execz .LBB0_538
	s_mov_b32 s0, 1
	s_mov_b64 s[62:63], 0
	v_mov_b32_e32 v0, 0
	s_branch .LBB0_529

; __device__ __forceinline__ unsigned xb_ld(unsigned* p)              { return __hip_atomic_load(p, __ATOMIC_RELAXED, __HIP_MEMORY_SCOPE_AGENT); }
; __device__ __forceinline__ unsigned xb_add(unsigned* p, unsigned v) { return __hip_atomic_fetch_add(p, v, __ATOMIC_RELAXED, __HIP_MEMORY_SCOPE_AGENT); }
; #define XB_SPIN(cond, bar) do { unsigned _sp = 0; while (cond) { __builtin_amdgcn_s_sleep(1); \
;     if ((++_sp & 255u) == 0u) { if (xb_ld(&(bar)[XB_TMO])) break; if (_sp > XB_SPIN_CAP) { atomicAdd(&(bar)[XB_TMO], 1u); break; } } } } while (0)
; __device__ __forceinline__ void xcd_barrier(const XcdBarrier& b) {
;     ...
;         const unsigned old = xb_add(&bar[XB_XSUB(b.x)], 1u);
;         const unsigned gen = old / nloc;
;         if (old + 1u == (gen + 1u) * nloc) {
;             __builtin_amdgcn_fence(__ATOMIC_RELEASE, "agent");
;             asm volatile("s_waitcnt vmcnt(0)" ::: "memory");
;             const unsigned og = xb_add(&bar[XB_TOP], 1u);
;             const unsigned tg = og / nx;
;             if (og + 1u == (tg + 1u) * nx) xb_add(&bar[XB_TOPGEN], 1u);
;             else XB_SPIN(xb_ld(&bar[XB_TOPGEN]) == tg, bar);
;             __builtin_amdgcn_fence(__ATOMIC_ACQUIRE, "agent");
;             xb_add(&bar[XB_XGEN(b.x)], 1u);
;             asm volatile("s_waitcnt vmcnt(0)" ::: "memory");
;         } else {
;             XB_SPIN(xb_ld(&bar[XB_XGEN(b.x)]) == gen, bar);
.LBB0_2836:
	s_or_b64 exec, exec, s[10:11]
	v_cvt_f32_u32_e32 v4, v2
	s_waitcnt vmcnt(0)
	v_readfirstlane_b32 s2, v3
	v_sub_u32_e32 v3, 0, v2
	v_rcp_iflag_f32_e32 v4, v4
	v_add_u32_e32 v5, s2, v1
	v_mul_f32_e32 v4, 0x4f7ffffe, v4
	v_cvt_u32_f32_e32 v4, v4
	v_mul_lo_u32 v1, v3, v4
	v_mul_hi_u32 v1, v4, v1
	v_add_u32_e32 v1, v4, v1
	v_mul_hi_u32 v1, v5, v1
	v_mul_lo_u32 v3, v1, v2
	v_sub_u32_e32 v3, v5, v3
	v_add_u32_e32 v4, 1, v1
	v_cmp_ge_u32_e32 vcc, v3, v2
	s_nop 1
	v_cndmask_b32_e32 v1, v1, v4, vcc
	v_sub_u32_e32 v4, v3, v2
	v_cndmask_b32_e32 v3, v3, v4, vcc
	v_add_u32_e32 v4, 1, v1
	v_cmp_ge_u32_e32 vcc, v3, v2
	v_add_u32_e32 v3, 1, v5
	s_nop 0
	v_cndmask_b32_e32 v1, v1, v4, vcc
	v_mul_lo_u32 v4, v2, v1
	v_add_u32_e32 v2, v4, v2
	v_cmp_ne_u32_e32 vcc, v3, v2
	s_and_saveexec_b64 s[2:3], vcc
	s_xor_b64 s[8:9], exec, s[2:3]
	s_cbranch_execz .LBB0_2850
	s_waitcnt lgkmcnt(0)
	s_cmpk_gt_i32 s33, 0x80
	s_cbranch_scc0 .Lb2wait_l1
	s_cmp_gt_i32 s92, 63
	s_cbranch_scc1 .LBB0_2850
.Lb2wait_l1:
	v_mov_b32_e32 v0, 0x2000
	global_load_dword v0, v0, s[6:7] offset:1024 sc1
	s_add_u32 s12, s6, 0x2400
	s_addc_u32 s13, s7, 0
	s_waitcnt vmcnt(0)
	v_cmp_eq_u32_e32 vcc, v0, v1
	s_and_saveexec_b64 s[10:11], vcc
	s_cbranch_execz .LBB0_2849
	s_mov_b32 s2, 1
	s_mov_b64 s[30:31], 0
	v_mov_b32_e32 v0, 0
	s_branch .LBB0_2840
